# removed two dependency-free grid barriers (group-loop top before norm1; before rwkv_post)
# speedup vs baseline: 1.0642x; 1.0022x over previous
.LBB0_503:
	s_waitcnt vmcnt(0)
	s_waitcnt lgkmcnt(0)
	s_barrier
	s_and_saveexec_b64 s[0:1], s[74:75]
	s_branch .LBB0_556
	v_cmp_eq_u32_e32 vcc, 0, v154
	s_waitcnt vmcnt(0) expcnt(0) lgkmcnt(0)
	s_and_saveexec_b64 s[24:25], vcc
	s_cbranch_execz .LBB0_519
	s_mov_b32 s36, 1
	s_branch .LBB0_507

.LBB0_1059:
	s_andn2_b64 vcc, exec, s[78:79]
	s_cbranch_vccnz .LBB0_1117
	s_waitcnt vmcnt(0)
	s_barrier
	s_and_saveexec_b64 s[0:1], s[74:75]
	v_readlane_b32 s2, v241, 19
	s_branch .LBB0_1113
	v_cmp_eq_u32_e32 vcc, 0, v154
	s_waitcnt vmcnt(0) expcnt(0) lgkmcnt(0)
	s_and_saveexec_b64 s[24:25], vcc
	s_cbranch_execz .LBB0_1076
	s_mov_b32 s36, 1
	s_branch .LBB0_1064
